# P7 SwiGLU output stores marked sc0 sc1 (system-scope write-through) so less dirty L2 remains for the seam-7 write-back
# speedup vs baseline: 1.0009x; 1.0009x over previous
.LBB0_642:
	s_mov_b32 s98, 0xbfb8aa3b
	s_mov_b32 s99, 0xbfb8aa3b
	s_mov_b32 s100, 1.0
	s_mov_b32 s101, 1.0
	v_lshl_add_u32 v156, s65, 10, v151
	ds_read_b32 v158, v156
	v_lshl_or_b32 v146, s66, 7, v150
	v_lshl_add_u32 v155, s42, 8, v148
	v_ashrrev_i32_e32 v147, 31, v146
	v_mov_b64_e32 v[144:145], s[16:17]
	s_waitcnt lgkmcnt(0)
	v_pk_mul_f32 v[124:125], v[124:125], v[158:159] op_sel_hi:[1,0]
	v_pk_mul_f32 v[126:127], v[126:127], v[158:159] op_sel_hi:[1,0]
	v_pk_mul_f32 v[120:121], v[120:121], v[158:159] op_sel_hi:[1,0]
	v_pk_mul_f32 v[122:123], v[122:123], v[158:159] op_sel_hi:[1,0]
	v_pk_mul_f32 v[116:117], v[116:117], v[158:159] op_sel_hi:[1,0]
	v_pk_mul_f32 v[118:119], v[118:119], v[158:159] op_sel_hi:[1,0]
	v_pk_mul_f32 v[112:113], v[112:113], v[158:159] op_sel_hi:[1,0]
	v_pk_mul_f32 v[114:115], v[114:115], v[158:159] op_sel_hi:[1,0]
	v_pk_mul_f32 v[240:241], v[124:125], s[98:99] op_sel_hi:[1,0]
	v_pk_mul_f32 v[242:243], v[126:127], s[98:99] op_sel_hi:[1,0]
	v_pk_mul_f32 v[244:245], v[120:121], s[98:99] op_sel_hi:[1,0]
	v_pk_mul_f32 v[246:247], v[122:123], s[98:99] op_sel_hi:[1,0]
	v_exp_f32_e32 v240, v240
	v_exp_f32_e32 v241, v241
	v_exp_f32_e32 v242, v242
	v_exp_f32_e32 v243, v243
	v_exp_f32_e32 v244, v244
	v_exp_f32_e32 v245, v245
	v_exp_f32_e32 v246, v246
	v_exp_f32_e32 v247, v247
	v_pk_add_f32 v[240:241], v[240:241], s[100:101] op_sel_hi:[1,0]
	v_pk_add_f32 v[242:243], v[242:243], s[100:101] op_sel_hi:[1,0]
	v_pk_add_f32 v[244:245], v[244:245], s[100:101] op_sel_hi:[1,0]
	v_pk_add_f32 v[246:247], v[246:247], s[100:101] op_sel_hi:[1,0]
	v_rcp_f32_e32 v240, v240
	v_rcp_f32_e32 v241, v241
	v_rcp_f32_e32 v242, v242
	v_rcp_f32_e32 v243, v243
	v_rcp_f32_e32 v244, v244
	v_rcp_f32_e32 v245, v245
	v_rcp_f32_e32 v246, v246
	v_rcp_f32_e32 v247, v247
	v_pk_mul_f32 v[240:241], v[124:125], v[240:241]
	v_pk_mul_f32 v[242:243], v[126:127], v[242:243]
	v_pk_mul_f32 v[244:245], v[120:121], v[244:245]
	v_pk_mul_f32 v[246:247], v[122:123], v[246:247]
	v_pk_mul_f32 v[240:241], v[116:117], v[240:241]
	v_pk_mul_f32 v[242:243], v[118:119], v[242:243]
	v_pk_mul_f32 v[244:245], v[112:113], v[244:245]
	v_pk_mul_f32 v[246:247], v[114:115], v[246:247]
	v_cvt_pk_bf16_f32 v112, v240, v241
	v_cvt_pk_bf16_f32 v113, v242, v243
	v_cvt_pk_bf16_f32 v114, v244, v245
	v_cvt_pk_bf16_f32 v115, v246, v247
	v_mad_i64_i32 v[160:161], s[44:45], v155, s62, v[144:145]
	v_lshlrev_b64 v[146:147], 1, v[146:147]
	v_lshl_add_u64 v[160:161], v[160:161], 0, v[146:147]
	s_andn2_b64 vcc, exec, s[0:1]
	s_mov_b64 s[0:1], -1
	global_store_dwordx4 v[160:161], v[112:115], off sc0 sc1
	ds_read_b32 v112, v156 offset:64
	s_nop 0
	v_or_b32_e32 v113, 16, v155
	v_mad_i64_i32 v[114:115], s[44:45], v113, s62, v[144:145]
	s_waitcnt lgkmcnt(0)
	v_pk_mul_f32 v[108:109], v[108:109], v[112:113] op_sel_hi:[1,0]
	v_pk_mul_f32 v[110:111], v[110:111], v[112:113] op_sel_hi:[1,0]
	v_pk_mul_f32 v[104:105], v[104:105], v[112:113] op_sel_hi:[1,0]
	v_pk_mul_f32 v[106:107], v[106:107], v[112:113] op_sel_hi:[1,0]
	v_pk_mul_f32 v[100:101], v[100:101], v[112:113] op_sel_hi:[1,0]
	v_pk_mul_f32 v[102:103], v[102:103], v[112:113] op_sel_hi:[1,0]
	v_pk_mul_f32 v[96:97], v[96:97], v[112:113] op_sel_hi:[1,0]
	v_pk_mul_f32 v[98:99], v[98:99], v[112:113] op_sel_hi:[1,0]
	v_pk_mul_f32 v[240:241], v[108:109], s[98:99] op_sel_hi:[1,0]
	v_pk_mul_f32 v[242:243], v[110:111], s[98:99] op_sel_hi:[1,0]
	v_pk_mul_f32 v[244:245], v[104:105], s[98:99] op_sel_hi:[1,0]
	v_pk_mul_f32 v[246:247], v[106:107], s[98:99] op_sel_hi:[1,0]
	v_exp_f32_e32 v240, v240
	v_exp_f32_e32 v241, v241
	v_exp_f32_e32 v242, v242
	v_exp_f32_e32 v243, v243
	v_exp_f32_e32 v244, v244
	v_exp_f32_e32 v245, v245
	v_exp_f32_e32 v246, v246
	v_exp_f32_e32 v247, v247
	v_pk_add_f32 v[240:241], v[240:241], s[100:101] op_sel_hi:[1,0]
	v_pk_add_f32 v[242:243], v[242:243], s[100:101] op_sel_hi:[1,0]
	v_pk_add_f32 v[244:245], v[244:245], s[100:101] op_sel_hi:[1,0]
	v_pk_add_f32 v[246:247], v[246:247], s[100:101] op_sel_hi:[1,0]
	v_rcp_f32_e32 v240, v240
	v_rcp_f32_e32 v241, v241
	v_rcp_f32_e32 v242, v242
	v_rcp_f32_e32 v243, v243
	v_rcp_f32_e32 v244, v244
	v_rcp_f32_e32 v245, v245
	v_rcp_f32_e32 v246, v246
	v_rcp_f32_e32 v247, v247
	v_pk_mul_f32 v[240:241], v[108:109], v[240:241]
	v_pk_mul_f32 v[242:243], v[110:111], v[242:243]
	v_pk_mul_f32 v[244:245], v[104:105], v[244:245]
	v_pk_mul_f32 v[246:247], v[106:107], v[246:247]
	v_pk_mul_f32 v[240:241], v[100:101], v[240:241]
	v_pk_mul_f32 v[242:243], v[102:103], v[242:243]
	v_pk_mul_f32 v[244:245], v[96:97], v[244:245]
	v_pk_mul_f32 v[246:247], v[98:99], v[246:247]
	v_cvt_pk_bf16_f32 v96, v240, v241
	v_cvt_pk_bf16_f32 v97, v242, v243
	v_cvt_pk_bf16_f32 v98, v244, v245
	v_cvt_pk_bf16_f32 v99, v246, v247
	v_lshl_add_u64 v[114:115], v[114:115], 0, v[146:147]
	global_store_dwordx4 v[114:115], v[96:99], off sc0 sc1
	ds_read_b32 v96, v156 offset:128
	s_nop 0
	v_or_b32_e32 v97, 32, v155
	v_mad_i64_i32 v[98:99], s[44:45], v97, s62, v[144:145]
	s_waitcnt lgkmcnt(0)
	v_pk_mul_f32 v[92:93], v[92:93], v[96:97] op_sel_hi:[1,0]
	v_pk_mul_f32 v[94:95], v[94:95], v[96:97] op_sel_hi:[1,0]
	v_pk_mul_f32 v[88:89], v[88:89], v[96:97] op_sel_hi:[1,0]
	v_pk_mul_f32 v[90:91], v[90:91], v[96:97] op_sel_hi:[1,0]
	v_pk_mul_f32 v[84:85], v[84:85], v[96:97] op_sel_hi:[1,0]
	v_pk_mul_f32 v[86:87], v[86:87], v[96:97] op_sel_hi:[1,0]
	v_pk_mul_f32 v[80:81], v[80:81], v[96:97] op_sel_hi:[1,0]
	v_pk_mul_f32 v[82:83], v[82:83], v[96:97] op_sel_hi:[1,0]
	v_pk_mul_f32 v[240:241], v[92:93], s[98:99] op_sel_hi:[1,0]
	v_pk_mul_f32 v[242:243], v[94:95], s[98:99] op_sel_hi:[1,0]
	v_pk_mul_f32 v[244:245], v[88:89], s[98:99] op_sel_hi:[1,0]
	v_pk_mul_f32 v[246:247], v[90:91], s[98:99] op_sel_hi:[1,0]
	v_exp_f32_e32 v240, v240
	v_exp_f32_e32 v241, v241
	v_exp_f32_e32 v242, v242
	v_exp_f32_e32 v243, v243
	v_exp_f32_e32 v244, v244
	v_exp_f32_e32 v245, v245
	v_exp_f32_e32 v246, v246
	v_exp_f32_e32 v247, v247
	v_pk_add_f32 v[240:241], v[240:241], s[100:101] op_sel_hi:[1,0]
	v_pk_add_f32 v[242:243], v[242:243], s[100:101] op_sel_hi:[1,0]
	v_pk_add_f32 v[244:245], v[244:245], s[100:101] op_sel_hi:[1,0]
	v_pk_add_f32 v[246:247], v[246:247], s[100:101] op_sel_hi:[1,0]
	v_rcp_f32_e32 v240, v240
	v_rcp_f32_e32 v241, v241
	v_rcp_f32_e32 v242, v242
	v_rcp_f32_e32 v243, v243
	v_rcp_f32_e32 v244, v244
	v_rcp_f32_e32 v245, v245
	v_rcp_f32_e32 v246, v246
	v_rcp_f32_e32 v247, v247
	v_pk_mul_f32 v[240:241], v[92:93], v[240:241]
	v_pk_mul_f32 v[242:243], v[94:95], v[242:243]
	v_pk_mul_f32 v[244:245], v[88:89], v[244:245]
	v_pk_mul_f32 v[246:247], v[90:91], v[246:247]
	v_pk_mul_f32 v[240:241], v[84:85], v[240:241]
	v_pk_mul_f32 v[242:243], v[86:87], v[242:243]
	v_pk_mul_f32 v[244:245], v[80:81], v[244:245]
	v_pk_mul_f32 v[246:247], v[82:83], v[246:247]
	v_cvt_pk_bf16_f32 v80, v240, v241
	v_cvt_pk_bf16_f32 v81, v242, v243
	v_cvt_pk_bf16_f32 v82, v244, v245
	v_cvt_pk_bf16_f32 v83, v246, v247
	v_lshl_add_u64 v[98:99], v[98:99], 0, v[146:147]
	global_store_dwordx4 v[98:99], v[80:83], off sc0 sc1
	ds_read_b32 v80, v156 offset:192
	s_nop 0
	v_or_b32_e32 v81, 48, v155
	v_mad_i64_i32 v[82:83], s[44:45], v81, s62, v[144:145]
	s_waitcnt lgkmcnt(0)
	v_pk_mul_f32 v[76:77], v[76:77], v[80:81] op_sel_hi:[1,0]
	v_pk_mul_f32 v[78:79], v[78:79], v[80:81] op_sel_hi:[1,0]
	v_pk_mul_f32 v[72:73], v[72:73], v[80:81] op_sel_hi:[1,0]
	v_pk_mul_f32 v[74:75], v[74:75], v[80:81] op_sel_hi:[1,0]
	v_pk_mul_f32 v[68:69], v[68:69], v[80:81] op_sel_hi:[1,0]
	v_pk_mul_f32 v[70:71], v[70:71], v[80:81] op_sel_hi:[1,0]
	v_pk_mul_f32 v[64:65], v[64:65], v[80:81] op_sel_hi:[1,0]
	v_pk_mul_f32 v[66:67], v[66:67], v[80:81] op_sel_hi:[1,0]
	v_pk_mul_f32 v[240:241], v[76:77], s[98:99] op_sel_hi:[1,0]
	v_pk_mul_f32 v[242:243], v[78:79], s[98:99] op_sel_hi:[1,0]
	v_pk_mul_f32 v[244:245], v[72:73], s[98:99] op_sel_hi:[1,0]
	v_pk_mul_f32 v[246:247], v[74:75], s[98:99] op_sel_hi:[1,0]
	v_exp_f32_e32 v240, v240
	v_exp_f32_e32 v241, v241
	v_exp_f32_e32 v242, v242
	v_exp_f32_e32 v243, v243
	v_exp_f32_e32 v244, v244
	v_exp_f32_e32 v245, v245
	v_exp_f32_e32 v246, v246
	v_exp_f32_e32 v247, v247
	v_pk_add_f32 v[240:241], v[240:241], s[100:101] op_sel_hi:[1,0]
	v_pk_add_f32 v[242:243], v[242:243], s[100:101] op_sel_hi:[1,0]
	v_pk_add_f32 v[244:245], v[244:245], s[100:101] op_sel_hi:[1,0]
	v_pk_add_f32 v[246:247], v[246:247], s[100:101] op_sel_hi:[1,0]
	v_rcp_f32_e32 v240, v240
	v_rcp_f32_e32 v241, v241
	v_rcp_f32_e32 v242, v242
	v_rcp_f32_e32 v243, v243
	v_rcp_f32_e32 v244, v244
	v_rcp_f32_e32 v245, v245
	v_rcp_f32_e32 v246, v246
	v_rcp_f32_e32 v247, v247
	v_pk_mul_f32 v[240:241], v[76:77], v[240:241]
	v_pk_mul_f32 v[242:243], v[78:79], v[242:243]
	v_pk_mul_f32 v[244:245], v[72:73], v[244:245]
	v_pk_mul_f32 v[246:247], v[74:75], v[246:247]
	v_pk_mul_f32 v[240:241], v[68:69], v[240:241]
	v_pk_mul_f32 v[242:243], v[70:71], v[242:243]
	v_pk_mul_f32 v[244:245], v[64:65], v[244:245]
	v_pk_mul_f32 v[246:247], v[66:67], v[246:247]
	v_cvt_pk_bf16_f32 v64, v240, v241
	v_cvt_pk_bf16_f32 v65, v242, v243
	v_cvt_pk_bf16_f32 v66, v244, v245
	v_cvt_pk_bf16_f32 v67, v246, v247
	v_lshl_add_u64 v[82:83], v[82:83], 0, v[146:147]
	global_store_dwordx4 v[82:83], v[64:67], off sc0 sc1
	ds_read_b32 v64, v156 offset:512
	s_nop 0
	v_add_u32_e32 v65, 0x80, v155
	v_mad_i64_i32 v[66:67], s[44:45], v65, s62, v[144:145]
	s_waitcnt lgkmcnt(0)
	v_pk_mul_f32 v[60:61], v[60:61], v[64:65] op_sel_hi:[1,0]
	v_pk_mul_f32 v[62:63], v[62:63], v[64:65] op_sel_hi:[1,0]
	v_pk_mul_f32 v[56:57], v[56:57], v[64:65] op_sel_hi:[1,0]
	v_pk_mul_f32 v[58:59], v[58:59], v[64:65] op_sel_hi:[1,0]
	v_pk_mul_f32 v[52:53], v[52:53], v[64:65] op_sel_hi:[1,0]
	v_pk_mul_f32 v[54:55], v[54:55], v[64:65] op_sel_hi:[1,0]
	v_pk_mul_f32 v[48:49], v[48:49], v[64:65] op_sel_hi:[1,0]
	v_pk_mul_f32 v[50:51], v[50:51], v[64:65] op_sel_hi:[1,0]
	v_pk_mul_f32 v[240:241], v[60:61], s[98:99] op_sel_hi:[1,0]
	v_pk_mul_f32 v[242:243], v[62:63], s[98:99] op_sel_hi:[1,0]
	v_pk_mul_f32 v[244:245], v[56:57], s[98:99] op_sel_hi:[1,0]
	v_pk_mul_f32 v[246:247], v[58:59], s[98:99] op_sel_hi:[1,0]
	v_exp_f32_e32 v240, v240
	v_exp_f32_e32 v241, v241
	v_exp_f32_e32 v242, v242
	v_exp_f32_e32 v243, v243
	v_exp_f32_e32 v244, v244
	v_exp_f32_e32 v245, v245
	v_exp_f32_e32 v246, v246
	v_exp_f32_e32 v247, v247
	v_pk_add_f32 v[240:241], v[240:241], s[100:101] op_sel_hi:[1,0]
	v_pk_add_f32 v[242:243], v[242:243], s[100:101] op_sel_hi:[1,0]
	v_pk_add_f32 v[244:245], v[244:245], s[100:101] op_sel_hi:[1,0]
	v_pk_add_f32 v[246:247], v[246:247], s[100:101] op_sel_hi:[1,0]
	v_rcp_f32_e32 v240, v240
	v_rcp_f32_e32 v241, v241
	v_rcp_f32_e32 v242, v242
	v_rcp_f32_e32 v243, v243
	v_rcp_f32_e32 v244, v244
	v_rcp_f32_e32 v245, v245
	v_rcp_f32_e32 v246, v246
	v_rcp_f32_e32 v247, v247
	v_pk_mul_f32 v[240:241], v[60:61], v[240:241]
	v_pk_mul_f32 v[242:243], v[62:63], v[242:243]
	v_pk_mul_f32 v[244:245], v[56:57], v[244:245]
	v_pk_mul_f32 v[246:247], v[58:59], v[246:247]
	v_pk_mul_f32 v[240:241], v[52:53], v[240:241]
	v_pk_mul_f32 v[242:243], v[54:55], v[242:243]
	v_pk_mul_f32 v[244:245], v[48:49], v[244:245]
	v_pk_mul_f32 v[246:247], v[50:51], v[246:247]
	v_cvt_pk_bf16_f32 v48, v240, v241
	v_cvt_pk_bf16_f32 v49, v242, v243
	v_cvt_pk_bf16_f32 v50, v244, v245
	v_cvt_pk_bf16_f32 v51, v246, v247
	v_lshl_add_u64 v[66:67], v[66:67], 0, v[146:147]
	global_store_dwordx4 v[66:67], v[48:51], off sc0 sc1
	ds_read_b32 v48, v156 offset:576
	s_nop 0
	v_add_u32_e32 v49, 0x90, v155
	v_mad_i64_i32 v[50:51], s[44:45], v49, s62, v[144:145]
	s_waitcnt lgkmcnt(0)
	v_pk_mul_f32 v[44:45], v[44:45], v[48:49] op_sel_hi:[1,0]
	v_pk_mul_f32 v[46:47], v[46:47], v[48:49] op_sel_hi:[1,0]
	v_pk_mul_f32 v[40:41], v[40:41], v[48:49] op_sel_hi:[1,0]
	v_pk_mul_f32 v[42:43], v[42:43], v[48:49] op_sel_hi:[1,0]
	v_pk_mul_f32 v[36:37], v[36:37], v[48:49] op_sel_hi:[1,0]
	v_pk_mul_f32 v[38:39], v[38:39], v[48:49] op_sel_hi:[1,0]
	v_pk_mul_f32 v[32:33], v[32:33], v[48:49] op_sel_hi:[1,0]
	v_pk_mul_f32 v[34:35], v[34:35], v[48:49] op_sel_hi:[1,0]
	v_pk_mul_f32 v[240:241], v[44:45], s[98:99] op_sel_hi:[1,0]
	v_pk_mul_f32 v[242:243], v[46:47], s[98:99] op_sel_hi:[1,0]
	v_pk_mul_f32 v[244:245], v[40:41], s[98:99] op_sel_hi:[1,0]
	v_pk_mul_f32 v[246:247], v[42:43], s[98:99] op_sel_hi:[1,0]
	v_exp_f32_e32 v240, v240
	v_exp_f32_e32 v241, v241
	v_exp_f32_e32 v242, v242
	v_exp_f32_e32 v243, v243
	v_exp_f32_e32 v244, v244
	v_exp_f32_e32 v245, v245
	v_exp_f32_e32 v246, v246
	v_exp_f32_e32 v247, v247
	v_pk_add_f32 v[240:241], v[240:241], s[100:101] op_sel_hi:[1,0]
	v_pk_add_f32 v[242:243], v[242:243], s[100:101] op_sel_hi:[1,0]
	v_pk_add_f32 v[244:245], v[244:245], s[100:101] op_sel_hi:[1,0]
	v_pk_add_f32 v[246:247], v[246:247], s[100:101] op_sel_hi:[1,0]
	v_rcp_f32_e32 v240, v240
	v_rcp_f32_e32 v241, v241
	v_rcp_f32_e32 v242, v242
	v_rcp_f32_e32 v243, v243
	v_rcp_f32_e32 v244, v244
	v_rcp_f32_e32 v245, v245
	v_rcp_f32_e32 v246, v246
	v_rcp_f32_e32 v247, v247
	v_pk_mul_f32 v[240:241], v[44:45], v[240:241]
	v_pk_mul_f32 v[242:243], v[46:47], v[242:243]
	v_pk_mul_f32 v[244:245], v[40:41], v[244:245]
	v_pk_mul_f32 v[246:247], v[42:43], v[246:247]
	v_pk_mul_f32 v[240:241], v[36:37], v[240:241]
	v_pk_mul_f32 v[242:243], v[38:39], v[242:243]
	v_pk_mul_f32 v[244:245], v[32:33], v[244:245]
	v_pk_mul_f32 v[246:247], v[34:35], v[246:247]
	v_cvt_pk_bf16_f32 v32, v240, v241
	v_cvt_pk_bf16_f32 v33, v242, v243
	v_cvt_pk_bf16_f32 v34, v244, v245
	v_cvt_pk_bf16_f32 v35, v246, v247
	v_lshl_add_u64 v[50:51], v[50:51], 0, v[146:147]
	global_store_dwordx4 v[50:51], v[32:35], off sc0 sc1
	ds_read_b32 v32, v156 offset:640
	s_nop 0
	v_add_u32_e32 v33, 0xa0, v155
	v_mad_i64_i32 v[34:35], s[44:45], v33, s62, v[144:145]
	s_waitcnt lgkmcnt(0)
	v_pk_mul_f32 v[28:29], v[28:29], v[32:33] op_sel_hi:[1,0]
	v_pk_mul_f32 v[30:31], v[30:31], v[32:33] op_sel_hi:[1,0]
	v_pk_mul_f32 v[24:25], v[24:25], v[32:33] op_sel_hi:[1,0]
	v_pk_mul_f32 v[26:27], v[26:27], v[32:33] op_sel_hi:[1,0]
	v_pk_mul_f32 v[20:21], v[20:21], v[32:33] op_sel_hi:[1,0]
	v_pk_mul_f32 v[22:23], v[22:23], v[32:33] op_sel_hi:[1,0]
	v_pk_mul_f32 v[16:17], v[16:17], v[32:33] op_sel_hi:[1,0]
	v_pk_mul_f32 v[18:19], v[18:19], v[32:33] op_sel_hi:[1,0]
	v_pk_mul_f32 v[240:241], v[28:29], s[98:99] op_sel_hi:[1,0]
	v_pk_mul_f32 v[242:243], v[30:31], s[98:99] op_sel_hi:[1,0]
	v_pk_mul_f32 v[244:245], v[24:25], s[98:99] op_sel_hi:[1,0]
	v_pk_mul_f32 v[246:247], v[26:27], s[98:99] op_sel_hi:[1,0]
	v_exp_f32_e32 v240, v240
	v_exp_f32_e32 v241, v241
	v_exp_f32_e32 v242, v242
	v_exp_f32_e32 v243, v243
	v_exp_f32_e32 v244, v244
	v_exp_f32_e32 v245, v245
	v_exp_f32_e32 v246, v246
	v_exp_f32_e32 v247, v247
	v_pk_add_f32 v[240:241], v[240:241], s[100:101] op_sel_hi:[1,0]
	v_pk_add_f32 v[242:243], v[242:243], s[100:101] op_sel_hi:[1,0]
	v_pk_add_f32 v[244:245], v[244:245], s[100:101] op_sel_hi:[1,0]
	v_pk_add_f32 v[246:247], v[246:247], s[100:101] op_sel_hi:[1,0]
	v_rcp_f32_e32 v240, v240
	v_rcp_f32_e32 v241, v241
	v_rcp_f32_e32 v242, v242
	v_rcp_f32_e32 v243, v243
	v_rcp_f32_e32 v244, v244
	v_rcp_f32_e32 v245, v245
	v_rcp_f32_e32 v246, v246
	v_rcp_f32_e32 v247, v247
	v_pk_mul_f32 v[240:241], v[28:29], v[240:241]
	v_pk_mul_f32 v[242:243], v[30:31], v[242:243]
	v_pk_mul_f32 v[244:245], v[24:25], v[244:245]
	v_pk_mul_f32 v[246:247], v[26:27], v[246:247]
	v_pk_mul_f32 v[240:241], v[20:21], v[240:241]
	v_pk_mul_f32 v[242:243], v[22:23], v[242:243]
	v_pk_mul_f32 v[244:245], v[16:17], v[244:245]
	v_pk_mul_f32 v[246:247], v[18:19], v[246:247]
	v_cvt_pk_bf16_f32 v16, v240, v241
	v_cvt_pk_bf16_f32 v17, v242, v243
	v_cvt_pk_bf16_f32 v18, v244, v245
	v_cvt_pk_bf16_f32 v19, v246, v247
	v_lshl_add_u64 v[34:35], v[34:35], 0, v[146:147]
	global_store_dwordx4 v[34:35], v[16:19], off sc0 sc1
	ds_read_b32 v16, v156 offset:704
	s_nop 0
	v_add_u32_e32 v17, 0xb0, v155
	v_mad_i64_i32 v[18:19], s[44:45], v17, s62, v[144:145]
	s_waitcnt lgkmcnt(0)
	v_pk_mul_f32 v[12:13], v[12:13], v[16:17] op_sel_hi:[1,0]
	v_pk_mul_f32 v[14:15], v[14:15], v[16:17] op_sel_hi:[1,0]
	v_pk_mul_f32 v[8:9], v[8:9], v[16:17] op_sel_hi:[1,0]
	v_pk_mul_f32 v[10:11], v[10:11], v[16:17] op_sel_hi:[1,0]
	v_pk_mul_f32 v[4:5], v[4:5], v[16:17] op_sel_hi:[1,0]
	v_pk_mul_f32 v[6:7], v[6:7], v[16:17] op_sel_hi:[1,0]
	v_pk_mul_f32 v[0:1], v[0:1], v[16:17] op_sel_hi:[1,0]
	v_pk_mul_f32 v[2:3], v[2:3], v[16:17] op_sel_hi:[1,0]
	v_pk_mul_f32 v[240:241], v[12:13], s[98:99] op_sel_hi:[1,0]
	v_pk_mul_f32 v[242:243], v[14:15], s[98:99] op_sel_hi:[1,0]
	v_pk_mul_f32 v[244:245], v[8:9], s[98:99] op_sel_hi:[1,0]
	v_pk_mul_f32 v[246:247], v[10:11], s[98:99] op_sel_hi:[1,0]
	v_exp_f32_e32 v240, v240
	v_exp_f32_e32 v241, v241
	v_exp_f32_e32 v242, v242
	v_exp_f32_e32 v243, v243
	v_exp_f32_e32 v244, v244
	v_exp_f32_e32 v245, v245
	v_exp_f32_e32 v246, v246
	v_exp_f32_e32 v247, v247
	v_pk_add_f32 v[240:241], v[240:241], s[100:101] op_sel_hi:[1,0]
	v_pk_add_f32 v[242:243], v[242:243], s[100:101] op_sel_hi:[1,0]
	v_pk_add_f32 v[244:245], v[244:245], s[100:101] op_sel_hi:[1,0]
	v_pk_add_f32 v[246:247], v[246:247], s[100:101] op_sel_hi:[1,0]
	v_rcp_f32_e32 v240, v240
	v_rcp_f32_e32 v241, v241
	v_rcp_f32_e32 v242, v242
	v_rcp_f32_e32 v243, v243
	v_rcp_f32_e32 v244, v244
	v_rcp_f32_e32 v245, v245
	v_rcp_f32_e32 v246, v246
	v_rcp_f32_e32 v247, v247
	v_pk_mul_f32 v[240:241], v[12:13], v[240:241]
	v_pk_mul_f32 v[242:243], v[14:15], v[242:243]
	v_pk_mul_f32 v[244:245], v[8:9], v[244:245]
	v_pk_mul_f32 v[246:247], v[10:11], v[246:247]
	v_pk_mul_f32 v[240:241], v[4:5], v[240:241]
	v_pk_mul_f32 v[242:243], v[6:7], v[242:243]
	v_pk_mul_f32 v[244:245], v[0:1], v[244:245]
	v_pk_mul_f32 v[246:247], v[2:3], v[246:247]
	v_cvt_pk_bf16_f32 v0, v240, v241
	v_cvt_pk_bf16_f32 v1, v242, v243
	v_cvt_pk_bf16_f32 v2, v244, v245
	v_cvt_pk_bf16_f32 v3, v246, v247
	v_lshl_add_u64 v[18:19], v[18:19], 0, v[146:147]
	global_store_dwordx4 v[18:19], v[0:3], off sc0 sc1
	s_cbranch_vccnz .LBB0_635
	s_andn2_b64 vcc, exec, s[4:5]
	s_cbranch_vccnz .LBB0_634
	s_barrier
	s_branch .LBB0_634
